# EpiUp rewrite, variant: conv row neighbours folded in by v_fmac_f32_dpp (row_shr:1 / row_shl:1 + shift-by-15 for the block-edge lane) instead of DPP moves + pk_fma: 725 instr
# speedup vs baseline: 1.0121x; 1.0018x over previous
; __device__ __forceinline__ int tid_from(int wave) { return (wave << 6) | lane_now(); }
; #define GAS __attribute__((address_space(1)))
; template <int CTRL> __device__ __forceinline__ float dpp_ror(float v) { return __builtin_bit_cast(float, __builtin_amdgcn_update_dpp(0, __builtin_bit_cast(int, v), CTRL, 0xf, 0xf, false)); }
;     __device__ __forceinline__ void operator()(pg8::f32x4 (&acc)[2][2][4][2], const pg8::Unit& u, int wr_, int wc_, int fr_, int fq_) const {
;         int t_ = tid_from(wr_ * 4 + wc_); asm volatile("" : "+v"(t_));
;         const int fr = t_ & 15, fq = (t_ >> 4) & 3, wc = (t_ >> 6) & 3, wr = t_ >> 8; (void)wr_; (void)wc_; (void)fr_; (void)fq_;
;         const unsigned hc0 = (unsigned)(u.pn * 128 + wc * 32 + 8 * fq);
;         const bool e0 = fr == 0, e3 = fr == 15;
;         __builtin_amdgcn_sched_barrier(0);
; #pragma unroll
;         for (int ai = 0; ai < 2; ++ai) {
;             const int rbase = u.pm * 256 + ai * 128 + wr * 64;
;             const unsigned eb0 = (unsigned)((rbase >> 6) << 1) * (unsigned)DFF, eb3 = eb0 + (unsigned)DFF;
; #pragma unroll
;             for (int n = 0; n < 2; ++n) {
;                 const unsigned hc = hc0 + 4u * (unsigned)n;
;                 const pg8::f32x4 w0 = *(const GAS pg8::f32x4*)&cw[hc], w1 = *(const GAS pg8::f32x4*)&cw[(unsigned)DFF + hc], w2 = *(const GAS pg8::f32x4*)&cw[2u * (unsigned)DFF + hc], bb = *(const GAS pg8::f32x4*)&cb[hc];
;                 if (e0) { *(GAS pg8::f32x4*)&EG[eb0 + hc] = acc[ai][0][0][n]; *(GAS pg8::f32x4*)&EU[eb0 + hc] = acc[ai][1][0][n]; }
;                 if (e3) { *(GAS pg8::f32x4*)&EG[eb3 + hc] = acc[ai][0][3][n]; *(GAS pg8::f32x4*)&EU[eb3 + hc] = acc[ai][1][3][n]; }
; #pragma unroll
;                 for (int j = 0; j < 4; ++j) {
;                     float pr[4], nx[4], gg[4];
; #pragma unroll
;                     for (int m = 0; m < 4; ++m) { gg[m] = acc[ai][0][m][n][j]; pr[m] = dpp_ror<0x121>(gg[m]); nx[m] = dpp_ror<0x12F>(gg[m]); }
; #pragma unroll
;                     for (int m = 0; m < 4; ++m) {
;                         const float pv = fr > 0 ? pr[m] : (m > 0 ? pr[m > 0 ? m - 1 : 0] : 0.f);
;                         const float nv = fr < 15 ? nx[m] : (m < 3 ? nx[m < 3 ? m + 1 : 3] : 0.f);
;                         const float cv = w0[j] * pv + w1[j] * gg[m] + w2[j] * nv + bb[j];
.LBB0_1454:
	s_mov_b32 s92, s57
	s_mov_b32 s57, s94
	s_mov_b32 s93, s52
	v_mbcnt_lo_u32_b32 v235, -1, 0
	v_mbcnt_hi_u32_b32 v235, -1, v235
	v_mov_b32_e32 v172, 0xc0135761
	v_or_b32_e32 v235, s75, v235
	v_mov_b32_e32 v173, 0xc0135761
	v_and_b32_e32 v248, 15, v235
	v_lshrrev_b32_e32 v176, 1, v235
	v_ashrrev_i32_e32 v249, 2, v235
	v_and_b32_e32 v176, 0x78, v176
	v_and_b32_e32 v249, 0xffffffc0, v249
	v_lshl_or_b32 v176, s10, 7, v176
	v_lshl_add_u32 v249, s8, 8, v249
	v_cmp_eq_u32_e64 s[12:13], 0, v248
	v_cmp_eq_u32_e64 s[30:31], 15, v248
	v_cmp_ne_u32_e64 s[10:11], 0, v248
	v_cmp_ne_u32_e64 s[62:63], 15, v248
	v_add_u32_e32 v233, v249, v248
	v_lshrrev_b32_e32 v232, 5, v249
	s_movk_i32 s8, 0x1600
	v_mul_lo_u32 v233, v233, s8
	v_mul_lo_u32 v232, v232, s8
	v_add_u32_e32 v233, v233, v176
	v_add_u32_e32 v232, v232, v176
	v_lshlrev_b32_e32 v176, 2, v176
	v_lshlrev_b32_e32 v233, 1, v233
	v_lshlrev_b32_e32 v232, 2, v232
	v_add_u32_e32 v218, 0x5800, v176
	v_add_u32_e32 v219, 0xb000, v176
	global_load_dwordx4 v[120:123], v176, s[24:25] offset:0
	global_load_dwordx4 v[124:127], v218, s[24:25] offset:0
	global_load_dwordx4 v[128:131], v219, s[24:25] offset:0
	global_load_dwordx4 v[132:135], v176, s[26:27] offset:0
	global_load_dwordx4 v[178:181], v176, s[24:25] offset:16
	global_load_dwordx4 v[182:185], v218, s[24:25] offset:16
	global_load_dwordx4 v[186:189], v219, s[24:25] offset:16
	global_load_dwordx4 v[190:193], v176, s[26:27] offset:16
	v_mov_b32_e32 v174, 0xbdd2d3e7
	v_mov_b32_e32 v175, 0xbdd2d3e7
	v_mov_b32_e32 v210, 1.0
	v_mov_b32_e32 v211, 1.0
	s_mov_b64 s[8:9], exec
	s_waitcnt vmcnt(0)
	v_pk_fma_f32 v[194:195], v[124:125], v[140:141], v[132:133]
	v_pk_fma_f32 v[196:197], v[126:127], v[142:143], v[134:135]
	v_pk_fma_f32 v[198:199], v[124:125], v[84:85], v[132:133]
	v_pk_fma_f32 v[200:201], v[126:127], v[86:87], v[134:135]
	v_pk_fma_f32 v[202:203], v[124:125], v[80:81], v[132:133]
	v_pk_fma_f32 v[204:205], v[126:127], v[82:83], v[134:135]
	v_pk_fma_f32 v[206:207], v[124:125], v[136:137], v[132:133]
	v_pk_fma_f32 v[208:209], v[126:127], v[138:139], v[134:135]
	v_fmac_f32_dpp v194, v140, v120 row_shr:1 row_mask:0xf bank_mask:0xf
	v_fmac_f32_dpp v195, v141, v121 row_shr:1 row_mask:0xf bank_mask:0xf
	v_fmac_f32_dpp v196, v142, v122 row_shr:1 row_mask:0xf bank_mask:0xf
	v_fmac_f32_dpp v197, v143, v123 row_shr:1 row_mask:0xf bank_mask:0xf
	v_fmac_f32_dpp v198, v84, v120 row_shr:1 row_mask:0xf bank_mask:0xf
	v_fmac_f32_dpp v199, v85, v121 row_shr:1 row_mask:0xf bank_mask:0xf
	v_fmac_f32_dpp v200, v86, v122 row_shr:1 row_mask:0xf bank_mask:0xf
	v_fmac_f32_dpp v201, v87, v123 row_shr:1 row_mask:0xf bank_mask:0xf
	v_fmac_f32_dpp v202, v80, v120 row_shr:1 row_mask:0xf bank_mask:0xf
	v_fmac_f32_dpp v203, v81, v121 row_shr:1 row_mask:0xf bank_mask:0xf
	v_fmac_f32_dpp v204, v82, v122 row_shr:1 row_mask:0xf bank_mask:0xf
	v_fmac_f32_dpp v205, v83, v123 row_shr:1 row_mask:0xf bank_mask:0xf
	v_fmac_f32_dpp v206, v136, v120 row_shr:1 row_mask:0xf bank_mask:0xf
	v_fmac_f32_dpp v207, v137, v121 row_shr:1 row_mask:0xf bank_mask:0xf
	v_fmac_f32_dpp v208, v138, v122 row_shr:1 row_mask:0xf bank_mask:0xf
	v_fmac_f32_dpp v209, v139, v123 row_shr:1 row_mask:0xf bank_mask:0xf
	v_fmac_f32_dpp v194, v140, v128 row_shl:1 row_mask:0xf bank_mask:0xf
	v_fmac_f32_dpp v195, v141, v129 row_shl:1 row_mask:0xf bank_mask:0xf
	v_fmac_f32_dpp v196, v142, v130 row_shl:1 row_mask:0xf bank_mask:0xf
	v_fmac_f32_dpp v197, v143, v131 row_shl:1 row_mask:0xf bank_mask:0xf
	v_fmac_f32_dpp v198, v84, v128 row_shl:1 row_mask:0xf bank_mask:0xf
	v_fmac_f32_dpp v199, v85, v129 row_shl:1 row_mask:0xf bank_mask:0xf
	v_fmac_f32_dpp v200, v86, v130 row_shl:1 row_mask:0xf bank_mask:0xf
	v_fmac_f32_dpp v201, v87, v131 row_shl:1 row_mask:0xf bank_mask:0xf
	v_fmac_f32_dpp v202, v80, v128 row_shl:1 row_mask:0xf bank_mask:0xf
	v_fmac_f32_dpp v203, v81, v129 row_shl:1 row_mask:0xf bank_mask:0xf
	v_fmac_f32_dpp v204, v82, v130 row_shl:1 row_mask:0xf bank_mask:0xf
	v_fmac_f32_dpp v205, v83, v131 row_shl:1 row_mask:0xf bank_mask:0xf
	v_fmac_f32_dpp v206, v136, v128 row_shl:1 row_mask:0xf bank_mask:0xf
	v_fmac_f32_dpp v207, v137, v129 row_shl:1 row_mask:0xf bank_mask:0xf
	v_fmac_f32_dpp v208, v138, v130 row_shl:1 row_mask:0xf bank_mask:0xf
	v_fmac_f32_dpp v209, v139, v131 row_shl:1 row_mask:0xf bank_mask:0xf
	v_fmac_f32_dpp v198, v140, v120 row_shl:15 row_mask:0xf bank_mask:0xf
	v_fmac_f32_dpp v199, v141, v121 row_shl:15 row_mask:0xf bank_mask:0xf
	v_fmac_f32_dpp v200, v142, v122 row_shl:15 row_mask:0xf bank_mask:0xf
	v_fmac_f32_dpp v201, v143, v123 row_shl:15 row_mask:0xf bank_mask:0xf
	v_fmac_f32_dpp v202, v84, v120 row_shl:15 row_mask:0xf bank_mask:0xf
	v_fmac_f32_dpp v203, v85, v121 row_shl:15 row_mask:0xf bank_mask:0xf
	v_fmac_f32_dpp v204, v86, v122 row_shl:15 row_mask:0xf bank_mask:0xf
	v_fmac_f32_dpp v205, v87, v123 row_shl:15 row_mask:0xf bank_mask:0xf
	v_fmac_f32_dpp v206, v80, v120 row_shl:15 row_mask:0xf bank_mask:0xf
	v_fmac_f32_dpp v207, v81, v121 row_shl:15 row_mask:0xf bank_mask:0xf
	v_fmac_f32_dpp v208, v82, v122 row_shl:15 row_mask:0xf bank_mask:0xf
	v_fmac_f32_dpp v209, v83, v123 row_shl:15 row_mask:0xf bank_mask:0xf
	v_fmac_f32_dpp v194, v84, v128 row_shr:15 row_mask:0xf bank_mask:0xf
	v_fmac_f32_dpp v195, v85, v129 row_shr:15 row_mask:0xf bank_mask:0xf
	v_fmac_f32_dpp v196, v86, v130 row_shr:15 row_mask:0xf bank_mask:0xf
	v_fmac_f32_dpp v197, v87, v131 row_shr:15 row_mask:0xf bank_mask:0xf
	v_fmac_f32_dpp v198, v80, v128 row_shr:15 row_mask:0xf bank_mask:0xf
	v_fmac_f32_dpp v199, v81, v129 row_shr:15 row_mask:0xf bank_mask:0xf
	v_fmac_f32_dpp v200, v82, v130 row_shr:15 row_mask:0xf bank_mask:0xf
; #define GAS __attribute__((address_space(1)))
; template <int CTRL> __device__ __forceinline__ float dpp_ror(float v) { return __builtin_bit_cast(float, __builtin_amdgcn_update_dpp(0, __builtin_bit_cast(int, v), CTRL, 0xf, 0xf, false)); }
;     __device__ __forceinline__ void operator()(pg8::f32x4 (&acc)[2][2][4][2], const pg8::Unit& u, int wr_, int wc_, int fr_, int fq_) const {
;     ...
;                 if (e0) { *(GAS pg8::f32x4*)&EG[eb0 + hc] = acc[ai][0][0][n]; *(GAS pg8::f32x4*)&EU[eb0 + hc] = acc[ai][1][0][n]; }
;                 if (e3) { *(GAS pg8::f32x4*)&EG[eb3 + hc] = acc[ai][0][3][n]; *(GAS pg8::f32x4*)&EU[eb3 + hc] = acc[ai][1][3][n]; }
; #pragma unroll
;                 for (int j = 0; j < 4; ++j) {
;                     float pr[4], nx[4], gg[4];
; #pragma unroll
;                     for (int m = 0; m < 4; ++m) { gg[m] = acc[ai][0][m][n][j]; pr[m] = dpp_ror<0x121>(gg[m]); nx[m] = dpp_ror<0x12F>(gg[m]); }
; #pragma unroll
;                     for (int m = 0; m < 4; ++m) {
;                         const float pv = fr > 0 ? pr[m] : (m > 0 ? pr[m > 0 ? m - 1 : 0] : 0.f);
;                         const float nv = fr < 15 ? nx[m] : (m < 3 ? nx[m < 3 ? m + 1 : 3] : 0.f);
;                         const float cv = w0[j] * pv + w1[j] * gg[m] + w2[j] * nv + bb[j];
;                         if (m == 0) { if (e0) EP[eb0 + hc + (unsigned)j] = cv; } if (m == 3) { if (e3) EP[eb3 + hc + (unsigned)j] = cv; }
;                         acc[ai][0][m][n][j] = gelu_tanh(cv) * acc[ai][1][m][n][j];
	v_fmac_f32_dpp v201, v83, v131 row_shr:15 row_mask:0xf bank_mask:0xf
	v_fmac_f32_dpp v202, v136, v128 row_shr:15 row_mask:0xf bank_mask:0xf
	v_fmac_f32_dpp v203, v137, v129 row_shr:15 row_mask:0xf bank_mask:0xf
	v_fmac_f32_dpp v204, v138, v130 row_shr:15 row_mask:0xf bank_mask:0xf
	v_fmac_f32_dpp v205, v139, v131 row_shr:15 row_mask:0xf bank_mask:0xf
	v_mov_b32_e32 v235, v232
	s_mov_b64 exec, s[12:13]
	global_store_dwordx4 v235, v[140:143], s[16:17] offset:0
	global_store_dwordx4 v235, v[104:107], s[22:23] offset:0
	global_store_dwordx4 v235, v[194:197], s[20:21] offset:0
	s_mov_b64 exec, s[8:9]
	v_add_u32_e32 v235, 0x5800, v235
	s_mov_b64 exec, s[30:31]
	global_store_dwordx4 v235, v[136:139], s[16:17] offset:0
	global_store_dwordx4 v235, v[64:67], s[22:23] offset:0
	global_store_dwordx4 v235, v[206:209], s[20:21] offset:0
	s_mov_b64 exec, s[8:9]
	v_pk_mul_f32 v[144:145], v[194:195], v[194:195]
	v_pk_mul_f32 v[146:147], v[196:197], v[196:197]
	v_pk_mul_f32 v[148:149], v[198:199], v[198:199]
	v_pk_mul_f32 v[150:151], v[200:201], v[200:201]
	v_pk_mul_f32 v[164:165], v[202:203], v[202:203]
	v_pk_mul_f32 v[166:167], v[204:205], v[204:205]
	v_pk_mul_f32 v[168:169], v[206:207], v[206:207]
	v_pk_mul_f32 v[170:171], v[208:209], v[208:209]
	v_pk_fma_f32 v[144:145], v[144:145], v[174:175], v[172:173]
	v_pk_fma_f32 v[146:147], v[146:147], v[174:175], v[172:173]
	v_pk_fma_f32 v[148:149], v[148:149], v[174:175], v[172:173]
	v_pk_fma_f32 v[150:151], v[150:151], v[174:175], v[172:173]
	v_pk_fma_f32 v[164:165], v[164:165], v[174:175], v[172:173]
	v_pk_fma_f32 v[166:167], v[166:167], v[174:175], v[172:173]
	v_pk_fma_f32 v[168:169], v[168:169], v[174:175], v[172:173]
	v_pk_fma_f32 v[170:171], v[170:171], v[174:175], v[172:173]
	v_pk_mul_f32 v[144:145], v[144:145], v[194:195]
	v_pk_mul_f32 v[146:147], v[146:147], v[196:197]
	v_pk_mul_f32 v[148:149], v[148:149], v[198:199]
	v_pk_mul_f32 v[150:151], v[150:151], v[200:201]
	v_pk_mul_f32 v[164:165], v[164:165], v[202:203]
	v_pk_mul_f32 v[166:167], v[166:167], v[204:205]
	v_pk_mul_f32 v[168:169], v[168:169], v[206:207]
	v_pk_mul_f32 v[170:171], v[170:171], v[208:209]
	v_exp_f32_e32 v144, v144
	v_exp_f32_e32 v146, v146
	v_exp_f32_e32 v148, v148
	v_exp_f32_e32 v150, v150
	v_exp_f32_e32 v164, v164
	v_exp_f32_e32 v166, v166
	v_exp_f32_e32 v168, v168
	v_exp_f32_e32 v170, v170
	v_exp_f32_e32 v145, v145
	v_exp_f32_e32 v147, v147
	v_exp_f32_e32 v149, v149
	v_exp_f32_e32 v151, v151
	v_exp_f32_e32 v165, v165
	v_exp_f32_e32 v167, v167
	v_exp_f32_e32 v169, v169
	v_exp_f32_e32 v171, v171
	v_pk_add_f32 v[144:145], v[144:145], v[210:211]
	v_pk_add_f32 v[146:147], v[146:147], v[210:211]
	v_pk_add_f32 v[148:149], v[148:149], v[210:211]
	v_pk_add_f32 v[150:151], v[150:151], v[210:211]
	v_pk_add_f32 v[164:165], v[164:165], v[210:211]
	v_pk_add_f32 v[166:167], v[166:167], v[210:211]
	v_pk_add_f32 v[168:169], v[168:169], v[210:211]
	v_pk_add_f32 v[170:171], v[170:171], v[210:211]
	v_rcp_f32_e32 v144, v144
	v_rcp_f32_e32 v146, v146
	v_rcp_f32_e32 v148, v148
	v_rcp_f32_e32 v150, v150
	v_rcp_f32_e32 v164, v164
	v_rcp_f32_e32 v166, v166
	v_rcp_f32_e32 v168, v168
	v_rcp_f32_e32 v170, v170
	v_rcp_f32_e32 v145, v145
	v_rcp_f32_e32 v147, v147
	v_rcp_f32_e32 v149, v149
	v_rcp_f32_e32 v151, v151
	v_rcp_f32_e32 v165, v165
	v_rcp_f32_e32 v167, v167
	v_rcp_f32_e32 v169, v169
	v_rcp_f32_e32 v171, v171
	v_pk_mul_f32 v[140:141], v[194:195], v[104:105]
	v_pk_mul_f32 v[142:143], v[196:197], v[106:107]
	v_pk_mul_f32 v[84:85], v[198:199], v[76:77]
	v_pk_mul_f32 v[86:87], v[200:201], v[78:79]
	v_pk_mul_f32 v[80:81], v[202:203], v[72:73]
	v_pk_mul_f32 v[82:83], v[204:205], v[74:75]
	v_pk_mul_f32 v[136:137], v[206:207], v[64:65]
	v_pk_mul_f32 v[138:139], v[208:209], v[66:67]
	v_pk_mul_f32 v[140:141], v[140:141], v[144:145]
	v_pk_mul_f32 v[142:143], v[142:143], v[146:147]
	v_pk_mul_f32 v[84:85], v[84:85], v[148:149]
	v_pk_mul_f32 v[86:87], v[86:87], v[150:151]
	v_pk_mul_f32 v[80:81], v[80:81], v[164:165]
	v_pk_mul_f32 v[82:83], v[82:83], v[166:167]
	v_pk_mul_f32 v[136:137], v[136:137], v[168:169]
	v_pk_mul_f32 v[138:139], v[138:139], v[170:171]
	v_pk_fma_f32 v[194:195], v[182:183], v[116:117], v[190:191]
	v_pk_fma_f32 v[196:197], v[184:185], v[118:119], v[192:193]
	v_pk_fma_f32 v[198:199], v[182:183], v[100:101], v[190:191]
	v_pk_fma_f32 v[200:201], v[184:185], v[102:103], v[192:193]
	v_pk_fma_f32 v[202:203], v[182:183], v[96:97], v[190:191]
	v_pk_fma_f32 v[204:205], v[184:185], v[98:99], v[192:193]
	v_pk_fma_f32 v[206:207], v[182:183], v[112:113], v[190:191]
	v_pk_fma_f32 v[208:209], v[184:185], v[114:115], v[192:193]
	v_fmac_f32_dpp v194, v116, v178 row_shr:1 row_mask:0xf bank_mask:0xf
	v_fmac_f32_dpp v195, v117, v179 row_shr:1 row_mask:0xf bank_mask:0xf
	v_fmac_f32_dpp v196, v118, v180 row_shr:1 row_mask:0xf bank_mask:0xf
	v_fmac_f32_dpp v197, v119, v181 row_shr:1 row_mask:0xf bank_mask:0xf
	v_fmac_f32_dpp v198, v100, v178 row_shr:1 row_mask:0xf bank_mask:0xf
	v_fmac_f32_dpp v199, v101, v179 row_shr:1 row_mask:0xf bank_mask:0xf
	v_fmac_f32_dpp v200, v102, v180 row_shr:1 row_mask:0xf bank_mask:0xf
	v_fmac_f32_dpp v201, v103, v181 row_shr:1 row_mask:0xf bank_mask:0xf
	v_fmac_f32_dpp v202, v96, v178 row_shr:1 row_mask:0xf bank_mask:0xf
	v_fmac_f32_dpp v203, v97, v179 row_shr:1 row_mask:0xf bank_mask:0xf
	v_fmac_f32_dpp v204, v98, v180 row_shr:1 row_mask:0xf bank_mask:0xf
	v_fmac_f32_dpp v205, v99, v181 row_shr:1 row_mask:0xf bank_mask:0xf
	v_fmac_f32_dpp v206, v112, v178 row_shr:1 row_mask:0xf bank_mask:0xf
	v_fmac_f32_dpp v207, v113, v179 row_shr:1 row_mask:0xf bank_mask:0xf
	v_fmac_f32_dpp v208, v114, v180 row_shr:1 row_mask:0xf bank_mask:0xf
; #define GAS __attribute__((address_space(1)))
; template <int CTRL> __device__ __forceinline__ float dpp_ror(float v) { return __builtin_bit_cast(float, __builtin_amdgcn_update_dpp(0, __builtin_bit_cast(int, v), CTRL, 0xf, 0xf, false)); }
;     __device__ __forceinline__ void operator()(pg8::f32x4 (&acc)[2][2][4][2], const pg8::Unit& u, int wr_, int wc_, int fr_, int fq_) const {
;     ...
;                 if (e0) { *(GAS pg8::f32x4*)&EG[eb0 + hc] = acc[ai][0][0][n]; *(GAS pg8::f32x4*)&EU[eb0 + hc] = acc[ai][1][0][n]; }
;                 if (e3) { *(GAS pg8::f32x4*)&EG[eb3 + hc] = acc[ai][0][3][n]; *(GAS pg8::f32x4*)&EU[eb3 + hc] = acc[ai][1][3][n]; }
; #pragma unroll
;                 for (int j = 0; j < 4; ++j) {
;                     float pr[4], nx[4], gg[4];
; #pragma unroll
;                     for (int m = 0; m < 4; ++m) { gg[m] = acc[ai][0][m][n][j]; pr[m] = dpp_ror<0x121>(gg[m]); nx[m] = dpp_ror<0x12F>(gg[m]); }
; #pragma unroll
;                     for (int m = 0; m < 4; ++m) {
;                         const float pv = fr > 0 ? pr[m] : (m > 0 ? pr[m > 0 ? m - 1 : 0] : 0.f);
;                         const float nv = fr < 15 ? nx[m] : (m < 3 ? nx[m < 3 ? m + 1 : 3] : 0.f);
;                         const float cv = w0[j] * pv + w1[j] * gg[m] + w2[j] * nv + bb[j];
;                         if (m == 0) { if (e0) EP[eb0 + hc + (unsigned)j] = cv; } if (m == 3) { if (e3) EP[eb3 + hc + (unsigned)j] = cv; }
;                         acc[ai][0][m][n][j] = gelu_tanh(cv) * acc[ai][1][m][n][j];
;                     }
;                 }
;                 asm volatile("" ::: "memory"); __builtin_amdgcn_sched_barrier(0);
	v_fmac_f32_dpp v209, v115, v181 row_shr:1 row_mask:0xf bank_mask:0xf
	v_fmac_f32_dpp v194, v116, v186 row_shl:1 row_mask:0xf bank_mask:0xf
	v_fmac_f32_dpp v195, v117, v187 row_shl:1 row_mask:0xf bank_mask:0xf
	v_fmac_f32_dpp v196, v118, v188 row_shl:1 row_mask:0xf bank_mask:0xf
	v_fmac_f32_dpp v197, v119, v189 row_shl:1 row_mask:0xf bank_mask:0xf
	v_fmac_f32_dpp v198, v100, v186 row_shl:1 row_mask:0xf bank_mask:0xf
	v_fmac_f32_dpp v199, v101, v187 row_shl:1 row_mask:0xf bank_mask:0xf
	v_fmac_f32_dpp v200, v102, v188 row_shl:1 row_mask:0xf bank_mask:0xf
	v_fmac_f32_dpp v201, v103, v189 row_shl:1 row_mask:0xf bank_mask:0xf
	v_fmac_f32_dpp v202, v96, v186 row_shl:1 row_mask:0xf bank_mask:0xf
	v_fmac_f32_dpp v203, v97, v187 row_shl:1 row_mask:0xf bank_mask:0xf
	v_fmac_f32_dpp v204, v98, v188 row_shl:1 row_mask:0xf bank_mask:0xf
	v_fmac_f32_dpp v205, v99, v189 row_shl:1 row_mask:0xf bank_mask:0xf
	v_fmac_f32_dpp v206, v112, v186 row_shl:1 row_mask:0xf bank_mask:0xf
	v_fmac_f32_dpp v207, v113, v187 row_shl:1 row_mask:0xf bank_mask:0xf
	v_fmac_f32_dpp v208, v114, v188 row_shl:1 row_mask:0xf bank_mask:0xf
	v_fmac_f32_dpp v209, v115, v189 row_shl:1 row_mask:0xf bank_mask:0xf
	v_fmac_f32_dpp v198, v116, v178 row_shl:15 row_mask:0xf bank_mask:0xf
	v_fmac_f32_dpp v199, v117, v179 row_shl:15 row_mask:0xf bank_mask:0xf
	v_fmac_f32_dpp v200, v118, v180 row_shl:15 row_mask:0xf bank_mask:0xf
	v_fmac_f32_dpp v201, v119, v181 row_shl:15 row_mask:0xf bank_mask:0xf
	v_fmac_f32_dpp v202, v100, v178 row_shl:15 row_mask:0xf bank_mask:0xf
	v_fmac_f32_dpp v203, v101, v179 row_shl:15 row_mask:0xf bank_mask:0xf
	v_fmac_f32_dpp v204, v102, v180 row_shl:15 row_mask:0xf bank_mask:0xf
	v_fmac_f32_dpp v205, v103, v181 row_shl:15 row_mask:0xf bank_mask:0xf
	v_fmac_f32_dpp v206, v96, v178 row_shl:15 row_mask:0xf bank_mask:0xf
	v_fmac_f32_dpp v207, v97, v179 row_shl:15 row_mask:0xf bank_mask:0xf
	v_fmac_f32_dpp v208, v98, v180 row_shl:15 row_mask:0xf bank_mask:0xf
	v_fmac_f32_dpp v209, v99, v181 row_shl:15 row_mask:0xf bank_mask:0xf
	v_fmac_f32_dpp v194, v100, v186 row_shr:15 row_mask:0xf bank_mask:0xf
	v_fmac_f32_dpp v195, v101, v187 row_shr:15 row_mask:0xf bank_mask:0xf
	v_fmac_f32_dpp v196, v102, v188 row_shr:15 row_mask:0xf bank_mask:0xf
	v_fmac_f32_dpp v197, v103, v189 row_shr:15 row_mask:0xf bank_mask:0xf
	v_fmac_f32_dpp v198, v96, v186 row_shr:15 row_mask:0xf bank_mask:0xf
	v_fmac_f32_dpp v199, v97, v187 row_shr:15 row_mask:0xf bank_mask:0xf
	v_fmac_f32_dpp v200, v98, v188 row_shr:15 row_mask:0xf bank_mask:0xf
	v_fmac_f32_dpp v201, v99, v189 row_shr:15 row_mask:0xf bank_mask:0xf
	v_fmac_f32_dpp v202, v112, v186 row_shr:15 row_mask:0xf bank_mask:0xf
	v_fmac_f32_dpp v203, v113, v187 row_shr:15 row_mask:0xf bank_mask:0xf
	v_fmac_f32_dpp v204, v114, v188 row_shr:15 row_mask:0xf bank_mask:0xf
	v_fmac_f32_dpp v205, v115, v189 row_shr:15 row_mask:0xf bank_mask:0xf
	v_mov_b32_e32 v235, v232
	s_mov_b64 exec, s[12:13]
	global_store_dwordx4 v235, v[116:119], s[16:17] offset:16
	global_store_dwordx4 v235, v[108:111], s[22:23] offset:16
	global_store_dwordx4 v235, v[194:197], s[20:21] offset:16
	s_mov_b64 exec, s[8:9]
	v_add_u32_e32 v235, 0x5800, v235
	s_mov_b64 exec, s[30:31]
	global_store_dwordx4 v235, v[112:115], s[16:17] offset:16
	global_store_dwordx4 v235, v[68:71], s[22:23] offset:16
	global_store_dwordx4 v235, v[206:209], s[20:21] offset:16
	s_mov_b64 exec, s[8:9]
	v_pk_mul_f32 v[144:145], v[194:195], v[194:195]
	v_pk_mul_f32 v[146:147], v[196:197], v[196:197]
	v_pk_mul_f32 v[148:149], v[198:199], v[198:199]
	v_pk_mul_f32 v[150:151], v[200:201], v[200:201]
	v_pk_mul_f32 v[164:165], v[202:203], v[202:203]
	v_pk_mul_f32 v[166:167], v[204:205], v[204:205]
	v_pk_mul_f32 v[168:169], v[206:207], v[206:207]
	v_pk_mul_f32 v[170:171], v[208:209], v[208:209]
	v_pk_fma_f32 v[144:145], v[144:145], v[174:175], v[172:173]
	v_pk_fma_f32 v[146:147], v[146:147], v[174:175], v[172:173]
	v_pk_fma_f32 v[148:149], v[148:149], v[174:175], v[172:173]
	v_pk_fma_f32 v[150:151], v[150:151], v[174:175], v[172:173]
	v_pk_fma_f32 v[164:165], v[164:165], v[174:175], v[172:173]
	v_pk_fma_f32 v[166:167], v[166:167], v[174:175], v[172:173]
	v_pk_fma_f32 v[168:169], v[168:169], v[174:175], v[172:173]
	v_pk_fma_f32 v[170:171], v[170:171], v[174:175], v[172:173]
	v_pk_mul_f32 v[144:145], v[144:145], v[194:195]
	v_pk_mul_f32 v[146:147], v[146:147], v[196:197]
	v_pk_mul_f32 v[148:149], v[148:149], v[198:199]
	v_pk_mul_f32 v[150:151], v[150:151], v[200:201]
	v_pk_mul_f32 v[164:165], v[164:165], v[202:203]
	v_pk_mul_f32 v[166:167], v[166:167], v[204:205]
	v_pk_mul_f32 v[168:169], v[168:169], v[206:207]
	v_pk_mul_f32 v[170:171], v[170:171], v[208:209]
	v_exp_f32_e32 v144, v144
	v_exp_f32_e32 v146, v146
	v_exp_f32_e32 v148, v148
	v_exp_f32_e32 v150, v150
	v_exp_f32_e32 v164, v164
	v_exp_f32_e32 v166, v166
	v_exp_f32_e32 v168, v168
	v_exp_f32_e32 v170, v170
	v_exp_f32_e32 v145, v145
	v_exp_f32_e32 v147, v147
	v_exp_f32_e32 v149, v149
	v_exp_f32_e32 v151, v151
	v_exp_f32_e32 v165, v165
	v_exp_f32_e32 v167, v167
	v_exp_f32_e32 v169, v169
	v_exp_f32_e32 v171, v171
	v_pk_add_f32 v[144:145], v[144:145], v[210:211]
	v_pk_add_f32 v[146:147], v[146:147], v[210:211]
	v_pk_add_f32 v[148:149], v[148:149], v[210:211]
	v_pk_add_f32 v[150:151], v[150:151], v[210:211]
	v_pk_add_f32 v[164:165], v[164:165], v[210:211]
	v_pk_add_f32 v[166:167], v[166:167], v[210:211]
	v_pk_add_f32 v[168:169], v[168:169], v[210:211]
	v_pk_add_f32 v[170:171], v[170:171], v[210:211]
	v_rcp_f32_e32 v144, v144
	v_rcp_f32_e32 v146, v146
	v_rcp_f32_e32 v148, v148
	v_rcp_f32_e32 v150, v150
	v_rcp_f32_e32 v164, v164
	v_rcp_f32_e32 v166, v166
; __device__ __forceinline__ unsigned cvt_pk_bf16(float lo, float hi) { unsigned r; asm volatile("v_cvt_pk_bf16_f32 %0, %1, %2" : "=v"(r) : "v"(lo), "v"(hi)); return r; }
; #define GAS __attribute__((address_space(1)))
; template <int CTRL> __device__ __forceinline__ float dpp_ror(float v) { return __builtin_bit_cast(float, __builtin_amdgcn_update_dpp(0, __builtin_bit_cast(int, v), CTRL, 0xf, 0xf, false)); }
;     __device__ __forceinline__ void operator()(pg8::f32x4 (&acc)[2][2][4][2], const pg8::Unit& u, int wr_, int wc_, int fr_, int fq_) const {
;     ...
;                 if (e0) { *(GAS pg8::f32x4*)&EG[eb0 + hc] = acc[ai][0][0][n]; *(GAS pg8::f32x4*)&EU[eb0 + hc] = acc[ai][1][0][n]; }
;                 if (e3) { *(GAS pg8::f32x4*)&EG[eb3 + hc] = acc[ai][0][3][n]; *(GAS pg8::f32x4*)&EU[eb3 + hc] = acc[ai][1][3][n]; }
; #pragma unroll
;                 for (int j = 0; j < 4; ++j) {
;                     float pr[4], nx[4], gg[4];
; #pragma unroll
;                     for (int m = 0; m < 4; ++m) { gg[m] = acc[ai][0][m][n][j]; pr[m] = dpp_ror<0x121>(gg[m]); nx[m] = dpp_ror<0x12F>(gg[m]); }
; #pragma unroll
;                     for (int m = 0; m < 4; ++m) {
;                         const float pv = fr > 0 ? pr[m] : (m > 0 ? pr[m > 0 ? m - 1 : 0] : 0.f);
;                         const float nv = fr < 15 ? nx[m] : (m < 3 ? nx[m < 3 ? m + 1 : 3] : 0.f);
;                         const float cv = w0[j] * pv + w1[j] * gg[m] + w2[j] * nv + bb[j];
;                         if (m == 0) { if (e0) EP[eb0 + hc + (unsigned)j] = cv; } if (m == 3) { if (e3) EP[eb3 + hc + (unsigned)j] = cv; }
;                         acc[ai][0][m][n][j] = gelu_tanh(cv) * acc[ai][1][m][n][j];
;                     }
;                 }
;                 asm volatile("" ::: "memory"); __builtin_amdgcn_sched_barrier(0);
;             }
; #pragma unroll
;             for (int m = 0; m < 4; ++m) {
;                 if (!((m == 0 && e0) || (m == 3 && e3))) {
;                     const pg8::f32x4 v0 = acc[ai][0][m][0], v1 = acc[ai][0][m][1];
;                     v4u w; w.x = pg8::cvt_pk_bf16(v0[0], v0[1]); w.y = pg8::cvt_pk_bf16(v0[2], v0[3]); w.z = pg8::cvt_pk_bf16(v1[0], v1[1]); w.w = pg8::cvt_pk_bf16(v1[2], v1[3]);
;                     *(GAS v4u*)&HID[(unsigned)(rbase + m * 16 + fr) * (unsigned)DFF + hc0] = w;
	v_rcp_f32_e32 v168, v168
	v_rcp_f32_e32 v170, v170
	v_rcp_f32_e32 v145, v145
	v_rcp_f32_e32 v147, v147
	v_rcp_f32_e32 v149, v149
	v_rcp_f32_e32 v151, v151
	v_rcp_f32_e32 v165, v165
	v_rcp_f32_e32 v167, v167
	v_rcp_f32_e32 v169, v169
	v_rcp_f32_e32 v171, v171
	v_pk_mul_f32 v[116:117], v[194:195], v[108:109]
	v_pk_mul_f32 v[118:119], v[196:197], v[110:111]
	v_pk_mul_f32 v[100:101], v[198:199], v[92:93]
	v_pk_mul_f32 v[102:103], v[200:201], v[94:95]
	v_pk_mul_f32 v[96:97], v[202:203], v[88:89]
	v_pk_mul_f32 v[98:99], v[204:205], v[90:91]
	v_pk_mul_f32 v[112:113], v[206:207], v[68:69]
	v_pk_mul_f32 v[114:115], v[208:209], v[70:71]
	v_pk_mul_f32 v[116:117], v[116:117], v[144:145]
	v_pk_mul_f32 v[118:119], v[118:119], v[146:147]
	v_pk_mul_f32 v[100:101], v[100:101], v[148:149]
	v_pk_mul_f32 v[102:103], v[102:103], v[150:151]
	v_pk_mul_f32 v[96:97], v[96:97], v[164:165]
	v_pk_mul_f32 v[98:99], v[98:99], v[166:167]
	v_pk_mul_f32 v[112:113], v[112:113], v[168:169]
	v_pk_mul_f32 v[114:115], v[114:115], v[170:171]
	v_cvt_pk_bf16_f32 v140, v140, v141
	v_cvt_pk_bf16_f32 v141, v142, v143
	v_cvt_pk_bf16_f32 v142, v116, v117
	v_cvt_pk_bf16_f32 v143, v118, v119
	v_cvt_pk_bf16_f32 v84, v84, v85
	v_cvt_pk_bf16_f32 v85, v86, v87
	v_cvt_pk_bf16_f32 v86, v100, v101
	v_cvt_pk_bf16_f32 v87, v102, v103
	v_cvt_pk_bf16_f32 v80, v80, v81
	v_cvt_pk_bf16_f32 v81, v82, v83
	v_cvt_pk_bf16_f32 v82, v96, v97
	v_cvt_pk_bf16_f32 v83, v98, v99
	v_cvt_pk_bf16_f32 v136, v136, v137
	v_cvt_pk_bf16_f32 v137, v138, v139
	v_cvt_pk_bf16_f32 v138, v112, v113
	v_cvt_pk_bf16_f32 v139, v114, v115
	v_mov_b32_e32 v235, v233
	s_mov_b64 exec, s[10:11]
	global_store_dwordx4 v235, v[140:143], s[18:19]
	s_mov_b64 exec, s[8:9]
	v_add_u32_e32 v235, 0x2c000, v233
	global_store_dwordx4 v235, v[84:87], s[18:19]
	v_add_u32_e32 v235, 0x58000, v233
	global_store_dwordx4 v235, v[80:83], s[18:19]
	v_add_u32_e32 v235, 0x84000, v233
	s_mov_b64 exec, s[62:63]
	global_store_dwordx4 v235, v[136:139], s[18:19]
	s_mov_b64 exec, s[8:9]
	v_pk_fma_f32 v[194:195], v[124:125], v[60:61], v[132:133]
	v_pk_fma_f32 v[196:197], v[126:127], v[62:63], v[134:135]
	v_pk_fma_f32 v[198:199], v[124:125], v[20:21], v[132:133]
	v_pk_fma_f32 v[200:201], v[126:127], v[22:23], v[134:135]
	v_pk_fma_f32 v[202:203], v[124:125], v[16:17], v[132:133]
	v_pk_fma_f32 v[204:205], v[126:127], v[18:19], v[134:135]
	v_pk_fma_f32 v[206:207], v[124:125], v[56:57], v[132:133]
	v_pk_fma_f32 v[208:209], v[126:127], v[58:59], v[134:135]
	v_fmac_f32_dpp v194, v60, v120 row_shr:1 row_mask:0xf bank_mask:0xf
	v_fmac_f32_dpp v195, v61, v121 row_shr:1 row_mask:0xf bank_mask:0xf
	v_fmac_f32_dpp v196, v62, v122 row_shr:1 row_mask:0xf bank_mask:0xf
	v_fmac_f32_dpp v197, v63, v123 row_shr:1 row_mask:0xf bank_mask:0xf
	v_fmac_f32_dpp v198, v20, v120 row_shr:1 row_mask:0xf bank_mask:0xf
	v_fmac_f32_dpp v199, v21, v121 row_shr:1 row_mask:0xf bank_mask:0xf
	v_fmac_f32_dpp v200, v22, v122 row_shr:1 row_mask:0xf bank_mask:0xf
	v_fmac_f32_dpp v201, v23, v123 row_shr:1 row_mask:0xf bank_mask:0xf
	v_fmac_f32_dpp v202, v16, v120 row_shr:1 row_mask:0xf bank_mask:0xf
	v_fmac_f32_dpp v203, v17, v121 row_shr:1 row_mask:0xf bank_mask:0xf
	v_fmac_f32_dpp v204, v18, v122 row_shr:1 row_mask:0xf bank_mask:0xf
	v_fmac_f32_dpp v205, v19, v123 row_shr:1 row_mask:0xf bank_mask:0xf
	v_fmac_f32_dpp v206, v56, v120 row_shr:1 row_mask:0xf bank_mask:0xf
	v_fmac_f32_dpp v207, v57, v121 row_shr:1 row_mask:0xf bank_mask:0xf
	v_fmac_f32_dpp v208, v58, v122 row_shr:1 row_mask:0xf bank_mask:0xf
	v_fmac_f32_dpp v209, v59, v123 row_shr:1 row_mask:0xf bank_mask:0xf
	v_fmac_f32_dpp v194, v60, v128 row_shl:1 row_mask:0xf bank_mask:0xf
	v_fmac_f32_dpp v195, v61, v129 row_shl:1 row_mask:0xf bank_mask:0xf
	v_fmac_f32_dpp v196, v62, v130 row_shl:1 row_mask:0xf bank_mask:0xf
	v_fmac_f32_dpp v197, v63, v131 row_shl:1 row_mask:0xf bank_mask:0xf
	v_fmac_f32_dpp v198, v20, v128 row_shl:1 row_mask:0xf bank_mask:0xf
	v_fmac_f32_dpp v199, v21, v129 row_shl:1 row_mask:0xf bank_mask:0xf
	v_fmac_f32_dpp v200, v22, v130 row_shl:1 row_mask:0xf bank_mask:0xf
	v_fmac_f32_dpp v201, v23, v131 row_shl:1 row_mask:0xf bank_mask:0xf
	v_fmac_f32_dpp v202, v16, v128 row_shl:1 row_mask:0xf bank_mask:0xf
	v_fmac_f32_dpp v203, v17, v129 row_shl:1 row_mask:0xf bank_mask:0xf
	v_fmac_f32_dpp v204, v18, v130 row_shl:1 row_mask:0xf bank_mask:0xf
	v_fmac_f32_dpp v205, v19, v131 row_shl:1 row_mask:0xf bank_mask:0xf
	v_fmac_f32_dpp v206, v56, v128 row_shl:1 row_mask:0xf bank_mask:0xf
	v_fmac_f32_dpp v207, v57, v129 row_shl:1 row_mask:0xf bank_mask:0xf
	v_fmac_f32_dpp v208, v58, v130 row_shl:1 row_mask:0xf bank_mask:0xf
	v_fmac_f32_dpp v209, v59, v131 row_shl:1 row_mask:0xf bank_mask:0xf
	v_fmac_f32_dpp v198, v60, v120 row_shl:15 row_mask:0xf bank_mask:0xf
	v_fmac_f32_dpp v199, v61, v121 row_shl:15 row_mask:0xf bank_mask:0xf
	v_fmac_f32_dpp v200, v62, v122 row_shl:15 row_mask:0xf bank_mask:0xf
	v_fmac_f32_dpp v201, v63, v123 row_shl:15 row_mask:0xf bank_mask:0xf
	v_fmac_f32_dpp v202, v20, v120 row_shl:15 row_mask:0xf bank_mask:0xf
	v_fmac_f32_dpp v203, v21, v121 row_shl:15 row_mask:0xf bank_mask:0xf
	v_fmac_f32_dpp v204, v22, v122 row_shl:15 row_mask:0xf bank_mask:0xf
	v_fmac_f32_dpp v205, v23, v123 row_shl:15 row_mask:0xf bank_mask:0xf
	v_fmac_f32_dpp v206, v16, v120 row_shl:15 row_mask:0xf bank_mask:0xf
	v_fmac_f32_dpp v207, v17, v121 row_shl:15 row_mask:0xf bank_mask:0xf
	v_fmac_f32_dpp v208, v18, v122 row_shl:15 row_mask:0xf bank_mask:0xf
	v_fmac_f32_dpp v209, v19, v123 row_shl:15 row_mask:0xf bank_mask:0xf
	v_fmac_f32_dpp v194, v20, v128 row_shr:15 row_mask:0xf bank_mask:0xf
	v_fmac_f32_dpp v195, v21, v129 row_shr:15 row_mask:0xf bank_mask:0xf
; #define GAS __attribute__((address_space(1)))
; template <int CTRL> __device__ __forceinline__ float dpp_ror(float v) { return __builtin_bit_cast(float, __builtin_amdgcn_update_dpp(0, __builtin_bit_cast(int, v), CTRL, 0xf, 0xf, false)); }
;     __device__ __forceinline__ void operator()(pg8::f32x4 (&acc)[2][2][4][2], const pg8::Unit& u, int wr_, int wc_, int fr_, int fq_) const {
;     ...
;                 if (e0) { *(GAS pg8::f32x4*)&EG[eb0 + hc] = acc[ai][0][0][n]; *(GAS pg8::f32x4*)&EU[eb0 + hc] = acc[ai][1][0][n]; }
;                 if (e3) { *(GAS pg8::f32x4*)&EG[eb3 + hc] = acc[ai][0][3][n]; *(GAS pg8::f32x4*)&EU[eb3 + hc] = acc[ai][1][3][n]; }
; #pragma unroll
;                 for (int j = 0; j < 4; ++j) {
;                     float pr[4], nx[4], gg[4];
; #pragma unroll
;                     for (int m = 0; m < 4; ++m) { gg[m] = acc[ai][0][m][n][j]; pr[m] = dpp_ror<0x121>(gg[m]); nx[m] = dpp_ror<0x12F>(gg[m]); }
; #pragma unroll
;                     for (int m = 0; m < 4; ++m) {
;                         const float pv = fr > 0 ? pr[m] : (m > 0 ? pr[m > 0 ? m - 1 : 0] : 0.f);
;                         const float nv = fr < 15 ? nx[m] : (m < 3 ? nx[m < 3 ? m + 1 : 3] : 0.f);
;                         const float cv = w0[j] * pv + w1[j] * gg[m] + w2[j] * nv + bb[j];
;                         if (m == 0) { if (e0) EP[eb0 + hc + (unsigned)j] = cv; } if (m == 3) { if (e3) EP[eb3 + hc + (unsigned)j] = cv; }
;                         acc[ai][0][m][n][j] = gelu_tanh(cv) * acc[ai][1][m][n][j];
	v_fmac_f32_dpp v196, v22, v130 row_shr:15 row_mask:0xf bank_mask:0xf
	v_fmac_f32_dpp v197, v23, v131 row_shr:15 row_mask:0xf bank_mask:0xf
	v_fmac_f32_dpp v198, v16, v128 row_shr:15 row_mask:0xf bank_mask:0xf
	v_fmac_f32_dpp v199, v17, v129 row_shr:15 row_mask:0xf bank_mask:0xf
	v_fmac_f32_dpp v200, v18, v130 row_shr:15 row_mask:0xf bank_mask:0xf
	v_fmac_f32_dpp v201, v19, v131 row_shr:15 row_mask:0xf bank_mask:0xf
	v_fmac_f32_dpp v202, v56, v128 row_shr:15 row_mask:0xf bank_mask:0xf
	v_fmac_f32_dpp v203, v57, v129 row_shr:15 row_mask:0xf bank_mask:0xf
	v_fmac_f32_dpp v204, v58, v130 row_shr:15 row_mask:0xf bank_mask:0xf
	v_fmac_f32_dpp v205, v59, v131 row_shr:15 row_mask:0xf bank_mask:0xf
	v_add_u32_e32 v235, 0x16000, v232
	s_mov_b64 exec, s[12:13]
	global_store_dwordx4 v235, v[60:63], s[16:17] offset:0
	global_store_dwordx4 v235, v[40:43], s[22:23] offset:0
	global_store_dwordx4 v235, v[194:197], s[20:21] offset:0
	s_mov_b64 exec, s[8:9]
	v_add_u32_e32 v235, 0x5800, v235
	s_mov_b64 exec, s[30:31]
	global_store_dwordx4 v235, v[56:59], s[16:17] offset:0
	global_store_dwordx4 v235, v[0:3], s[22:23] offset:0
	global_store_dwordx4 v235, v[206:209], s[20:21] offset:0
	s_mov_b64 exec, s[8:9]
	v_pk_mul_f32 v[144:145], v[194:195], v[194:195]
	v_pk_mul_f32 v[146:147], v[196:197], v[196:197]
	v_pk_mul_f32 v[148:149], v[198:199], v[198:199]
	v_pk_mul_f32 v[150:151], v[200:201], v[200:201]
	v_pk_mul_f32 v[164:165], v[202:203], v[202:203]
	v_pk_mul_f32 v[166:167], v[204:205], v[204:205]
	v_pk_mul_f32 v[168:169], v[206:207], v[206:207]
	v_pk_mul_f32 v[170:171], v[208:209], v[208:209]
	v_pk_fma_f32 v[144:145], v[144:145], v[174:175], v[172:173]
	v_pk_fma_f32 v[146:147], v[146:147], v[174:175], v[172:173]
	v_pk_fma_f32 v[148:149], v[148:149], v[174:175], v[172:173]
	v_pk_fma_f32 v[150:151], v[150:151], v[174:175], v[172:173]
	v_pk_fma_f32 v[164:165], v[164:165], v[174:175], v[172:173]
	v_pk_fma_f32 v[166:167], v[166:167], v[174:175], v[172:173]
	v_pk_fma_f32 v[168:169], v[168:169], v[174:175], v[172:173]
	v_pk_fma_f32 v[170:171], v[170:171], v[174:175], v[172:173]
	v_pk_mul_f32 v[144:145], v[144:145], v[194:195]
	v_pk_mul_f32 v[146:147], v[146:147], v[196:197]
	v_pk_mul_f32 v[148:149], v[148:149], v[198:199]
	v_pk_mul_f32 v[150:151], v[150:151], v[200:201]
	v_pk_mul_f32 v[164:165], v[164:165], v[202:203]
	v_pk_mul_f32 v[166:167], v[166:167], v[204:205]
	v_pk_mul_f32 v[168:169], v[168:169], v[206:207]
	v_pk_mul_f32 v[170:171], v[170:171], v[208:209]
	v_exp_f32_e32 v144, v144
	v_exp_f32_e32 v146, v146
	v_exp_f32_e32 v148, v148
	v_exp_f32_e32 v150, v150
	v_exp_f32_e32 v164, v164
	v_exp_f32_e32 v166, v166
	v_exp_f32_e32 v168, v168
	v_exp_f32_e32 v170, v170
	v_exp_f32_e32 v145, v145
	v_exp_f32_e32 v147, v147
	v_exp_f32_e32 v149, v149
	v_exp_f32_e32 v151, v151
	v_exp_f32_e32 v165, v165
	v_exp_f32_e32 v167, v167
	v_exp_f32_e32 v169, v169
	v_exp_f32_e32 v171, v171
	v_pk_add_f32 v[144:145], v[144:145], v[210:211]
	v_pk_add_f32 v[146:147], v[146:147], v[210:211]
	v_pk_add_f32 v[148:149], v[148:149], v[210:211]
	v_pk_add_f32 v[150:151], v[150:151], v[210:211]
	v_pk_add_f32 v[164:165], v[164:165], v[210:211]
	v_pk_add_f32 v[166:167], v[166:167], v[210:211]
	v_pk_add_f32 v[168:169], v[168:169], v[210:211]
	v_pk_add_f32 v[170:171], v[170:171], v[210:211]
	v_rcp_f32_e32 v144, v144
	v_rcp_f32_e32 v146, v146
	v_rcp_f32_e32 v148, v148
	v_rcp_f32_e32 v150, v150
	v_rcp_f32_e32 v164, v164
	v_rcp_f32_e32 v166, v166
	v_rcp_f32_e32 v168, v168
	v_rcp_f32_e32 v170, v170
	v_rcp_f32_e32 v145, v145
	v_rcp_f32_e32 v147, v147
	v_rcp_f32_e32 v149, v149
	v_rcp_f32_e32 v151, v151
	v_rcp_f32_e32 v165, v165
	v_rcp_f32_e32 v167, v167
	v_rcp_f32_e32 v169, v169
	v_rcp_f32_e32 v171, v171
	v_pk_mul_f32 v[60:61], v[194:195], v[40:41]
	v_pk_mul_f32 v[62:63], v[196:197], v[42:43]
	v_pk_mul_f32 v[20:21], v[198:199], v[12:13]
	v_pk_mul_f32 v[22:23], v[200:201], v[14:15]
	v_pk_mul_f32 v[16:17], v[202:203], v[8:9]
	v_pk_mul_f32 v[18:19], v[204:205], v[10:11]
	v_pk_mul_f32 v[56:57], v[206:207], v[0:1]
	v_pk_mul_f32 v[58:59], v[208:209], v[2:3]
	v_pk_mul_f32 v[60:61], v[60:61], v[144:145]
	v_pk_mul_f32 v[62:63], v[62:63], v[146:147]
	v_pk_mul_f32 v[20:21], v[20:21], v[148:149]
	v_pk_mul_f32 v[22:23], v[22:23], v[150:151]
	v_pk_mul_f32 v[16:17], v[16:17], v[164:165]
	v_pk_mul_f32 v[18:19], v[18:19], v[166:167]
	v_pk_mul_f32 v[56:57], v[56:57], v[168:169]
	v_pk_mul_f32 v[58:59], v[58:59], v[170:171]
	v_pk_fma_f32 v[194:195], v[182:183], v[52:53], v[190:191]
	v_pk_fma_f32 v[196:197], v[184:185], v[54:55], v[192:193]
	v_pk_fma_f32 v[198:199], v[182:183], v[36:37], v[190:191]
	v_pk_fma_f32 v[200:201], v[184:185], v[38:39], v[192:193]
	v_pk_fma_f32 v[202:203], v[182:183], v[32:33], v[190:191]
	v_pk_fma_f32 v[204:205], v[184:185], v[34:35], v[192:193]
	v_pk_fma_f32 v[206:207], v[182:183], v[48:49], v[190:191]
	v_pk_fma_f32 v[208:209], v[184:185], v[50:51], v[192:193]
	v_fmac_f32_dpp v194, v52, v178 row_shr:1 row_mask:0xf bank_mask:0xf
	v_fmac_f32_dpp v195, v53, v179 row_shr:1 row_mask:0xf bank_mask:0xf
	v_fmac_f32_dpp v196, v54, v180 row_shr:1 row_mask:0xf bank_mask:0xf
	v_fmac_f32_dpp v197, v55, v181 row_shr:1 row_mask:0xf bank_mask:0xf
	v_fmac_f32_dpp v198, v36, v178 row_shr:1 row_mask:0xf bank_mask:0xf
	v_fmac_f32_dpp v199, v37, v179 row_shr:1 row_mask:0xf bank_mask:0xf
	v_fmac_f32_dpp v200, v38, v180 row_shr:1 row_mask:0xf bank_mask:0xf
	v_fmac_f32_dpp v201, v39, v181 row_shr:1 row_mask:0xf bank_mask:0xf
	v_fmac_f32_dpp v202, v32, v178 row_shr:1 row_mask:0xf bank_mask:0xf
	v_fmac_f32_dpp v203, v33, v179 row_shr:1 row_mask:0xf bank_mask:0xf
	v_fmac_f32_dpp v204, v34, v180 row_shr:1 row_mask:0xf bank_mask:0xf
; #define GAS __attribute__((address_space(1)))
; template <int CTRL> __device__ __forceinline__ float dpp_ror(float v) { return __builtin_bit_cast(float, __builtin_amdgcn_update_dpp(0, __builtin_bit_cast(int, v), CTRL, 0xf, 0xf, false)); }
;     __device__ __forceinline__ void operator()(pg8::f32x4 (&acc)[2][2][4][2], const pg8::Unit& u, int wr_, int wc_, int fr_, int fq_) const {
;     ...
;                 if (e0) { *(GAS pg8::f32x4*)&EG[eb0 + hc] = acc[ai][0][0][n]; *(GAS pg8::f32x4*)&EU[eb0 + hc] = acc[ai][1][0][n]; }
;                 if (e3) { *(GAS pg8::f32x4*)&EG[eb3 + hc] = acc[ai][0][3][n]; *(GAS pg8::f32x4*)&EU[eb3 + hc] = acc[ai][1][3][n]; }
; #pragma unroll
;                 for (int j = 0; j < 4; ++j) {
;                     float pr[4], nx[4], gg[4];
; #pragma unroll
;                     for (int m = 0; m < 4; ++m) { gg[m] = acc[ai][0][m][n][j]; pr[m] = dpp_ror<0x121>(gg[m]); nx[m] = dpp_ror<0x12F>(gg[m]); }
; #pragma unroll
;                     for (int m = 0; m < 4; ++m) {
;                         const float pv = fr > 0 ? pr[m] : (m > 0 ? pr[m > 0 ? m - 1 : 0] : 0.f);
;                         const float nv = fr < 15 ? nx[m] : (m < 3 ? nx[m < 3 ? m + 1 : 3] : 0.f);
;                         const float cv = w0[j] * pv + w1[j] * gg[m] + w2[j] * nv + bb[j];
;                         if (m == 0) { if (e0) EP[eb0 + hc + (unsigned)j] = cv; } if (m == 3) { if (e3) EP[eb3 + hc + (unsigned)j] = cv; }
;                         acc[ai][0][m][n][j] = gelu_tanh(cv) * acc[ai][1][m][n][j];
	v_fmac_f32_dpp v205, v35, v181 row_shr:1 row_mask:0xf bank_mask:0xf
	v_fmac_f32_dpp v206, v48, v178 row_shr:1 row_mask:0xf bank_mask:0xf
	v_fmac_f32_dpp v207, v49, v179 row_shr:1 row_mask:0xf bank_mask:0xf
	v_fmac_f32_dpp v208, v50, v180 row_shr:1 row_mask:0xf bank_mask:0xf
	v_fmac_f32_dpp v209, v51, v181 row_shr:1 row_mask:0xf bank_mask:0xf
	v_fmac_f32_dpp v194, v52, v186 row_shl:1 row_mask:0xf bank_mask:0xf
	v_fmac_f32_dpp v195, v53, v187 row_shl:1 row_mask:0xf bank_mask:0xf
	v_fmac_f32_dpp v196, v54, v188 row_shl:1 row_mask:0xf bank_mask:0xf
	v_fmac_f32_dpp v197, v55, v189 row_shl:1 row_mask:0xf bank_mask:0xf
	v_fmac_f32_dpp v198, v36, v186 row_shl:1 row_mask:0xf bank_mask:0xf
	v_fmac_f32_dpp v199, v37, v187 row_shl:1 row_mask:0xf bank_mask:0xf
	v_fmac_f32_dpp v200, v38, v188 row_shl:1 row_mask:0xf bank_mask:0xf
	v_fmac_f32_dpp v201, v39, v189 row_shl:1 row_mask:0xf bank_mask:0xf
	v_fmac_f32_dpp v202, v32, v186 row_shl:1 row_mask:0xf bank_mask:0xf
	v_fmac_f32_dpp v203, v33, v187 row_shl:1 row_mask:0xf bank_mask:0xf
	v_fmac_f32_dpp v204, v34, v188 row_shl:1 row_mask:0xf bank_mask:0xf
	v_fmac_f32_dpp v205, v35, v189 row_shl:1 row_mask:0xf bank_mask:0xf
	v_fmac_f32_dpp v206, v48, v186 row_shl:1 row_mask:0xf bank_mask:0xf
	v_fmac_f32_dpp v207, v49, v187 row_shl:1 row_mask:0xf bank_mask:0xf
	v_fmac_f32_dpp v208, v50, v188 row_shl:1 row_mask:0xf bank_mask:0xf
	v_fmac_f32_dpp v209, v51, v189 row_shl:1 row_mask:0xf bank_mask:0xf
	v_fmac_f32_dpp v198, v52, v178 row_shl:15 row_mask:0xf bank_mask:0xf
	v_fmac_f32_dpp v199, v53, v179 row_shl:15 row_mask:0xf bank_mask:0xf
	v_fmac_f32_dpp v200, v54, v180 row_shl:15 row_mask:0xf bank_mask:0xf
	v_fmac_f32_dpp v201, v55, v181 row_shl:15 row_mask:0xf bank_mask:0xf
	v_fmac_f32_dpp v202, v36, v178 row_shl:15 row_mask:0xf bank_mask:0xf
	v_fmac_f32_dpp v203, v37, v179 row_shl:15 row_mask:0xf bank_mask:0xf
	v_fmac_f32_dpp v204, v38, v180 row_shl:15 row_mask:0xf bank_mask:0xf
	v_fmac_f32_dpp v205, v39, v181 row_shl:15 row_mask:0xf bank_mask:0xf
	v_fmac_f32_dpp v206, v32, v178 row_shl:15 row_mask:0xf bank_mask:0xf
	v_fmac_f32_dpp v207, v33, v179 row_shl:15 row_mask:0xf bank_mask:0xf
	v_fmac_f32_dpp v208, v34, v180 row_shl:15 row_mask:0xf bank_mask:0xf
	v_fmac_f32_dpp v209, v35, v181 row_shl:15 row_mask:0xf bank_mask:0xf
	v_fmac_f32_dpp v194, v36, v186 row_shr:15 row_mask:0xf bank_mask:0xf
	v_fmac_f32_dpp v195, v37, v187 row_shr:15 row_mask:0xf bank_mask:0xf
	v_fmac_f32_dpp v196, v38, v188 row_shr:15 row_mask:0xf bank_mask:0xf
	v_fmac_f32_dpp v197, v39, v189 row_shr:15 row_mask:0xf bank_mask:0xf
	v_fmac_f32_dpp v198, v32, v186 row_shr:15 row_mask:0xf bank_mask:0xf
	v_fmac_f32_dpp v199, v33, v187 row_shr:15 row_mask:0xf bank_mask:0xf
	v_fmac_f32_dpp v200, v34, v188 row_shr:15 row_mask:0xf bank_mask:0xf
	v_fmac_f32_dpp v201, v35, v189 row_shr:15 row_mask:0xf bank_mask:0xf
	v_fmac_f32_dpp v202, v48, v186 row_shr:15 row_mask:0xf bank_mask:0xf
	v_fmac_f32_dpp v203, v49, v187 row_shr:15 row_mask:0xf bank_mask:0xf
	v_fmac_f32_dpp v204, v50, v188 row_shr:15 row_mask:0xf bank_mask:0xf
	v_fmac_f32_dpp v205, v51, v189 row_shr:15 row_mask:0xf bank_mask:0xf
	v_add_u32_e32 v235, 0x16000, v232
	s_mov_b64 exec, s[12:13]
	global_store_dwordx4 v235, v[52:55], s[16:17] offset:16
	global_store_dwordx4 v235, v[44:47], s[22:23] offset:16
	global_store_dwordx4 v235, v[194:197], s[20:21] offset:16
	s_mov_b64 exec, s[8:9]
	v_add_u32_e32 v235, 0x5800, v235
	s_mov_b64 exec, s[30:31]
	global_store_dwordx4 v235, v[48:51], s[16:17] offset:16
	global_store_dwordx4 v235, v[4:7], s[22:23] offset:16
	global_store_dwordx4 v235, v[206:209], s[20:21] offset:16
	s_mov_b64 exec, s[8:9]
	v_pk_mul_f32 v[144:145], v[194:195], v[194:195]
	v_pk_mul_f32 v[146:147], v[196:197], v[196:197]
	v_pk_mul_f32 v[148:149], v[198:199], v[198:199]
	v_pk_mul_f32 v[150:151], v[200:201], v[200:201]
	v_pk_mul_f32 v[164:165], v[202:203], v[202:203]
; __device__ __forceinline__ unsigned cvt_pk_bf16(float lo, float hi) { unsigned r; asm volatile("v_cvt_pk_bf16_f32 %0, %1, %2" : "=v"(r) : "v"(lo), "v"(hi)); return r; }
; #define GAS __attribute__((address_space(1)))
;     __device__ __forceinline__ void operator()(pg8::f32x4 (&acc)[2][2][4][2], const pg8::Unit& u, int wr_, int wc_, int fr_, int fq_) const {
;     ...
;                         const float cv = w0[j] * pv + w1[j] * gg[m] + w2[j] * nv + bb[j];
;                         if (m == 0) { if (e0) EP[eb0 + hc + (unsigned)j] = cv; } if (m == 3) { if (e3) EP[eb3 + hc + (unsigned)j] = cv; }
;                         acc[ai][0][m][n][j] = gelu_tanh(cv) * acc[ai][1][m][n][j];
;                     }
;                 }
;                 asm volatile("" ::: "memory"); __builtin_amdgcn_sched_barrier(0);
;             }
; #pragma unroll
;             for (int m = 0; m < 4; ++m) {
;                 if (!((m == 0 && e0) || (m == 3 && e3))) {
;                     const pg8::f32x4 v0 = acc[ai][0][m][0], v1 = acc[ai][0][m][1];
;                     v4u w; w.x = pg8::cvt_pk_bf16(v0[0], v0[1]); w.y = pg8::cvt_pk_bf16(v0[2], v0[3]); w.z = pg8::cvt_pk_bf16(v1[0], v1[1]); w.w = pg8::cvt_pk_bf16(v1[2], v1[3]);
;                     *(GAS v4u*)&HID[(unsigned)(rbase + m * 16 + fr) * (unsigned)DFF + hc0] = w;
	v_pk_mul_f32 v[166:167], v[204:205], v[204:205]
	v_pk_mul_f32 v[168:169], v[206:207], v[206:207]
	v_pk_mul_f32 v[170:171], v[208:209], v[208:209]
	v_pk_fma_f32 v[144:145], v[144:145], v[174:175], v[172:173]
	v_pk_fma_f32 v[146:147], v[146:147], v[174:175], v[172:173]
	v_pk_fma_f32 v[148:149], v[148:149], v[174:175], v[172:173]
	v_pk_fma_f32 v[150:151], v[150:151], v[174:175], v[172:173]
	v_pk_fma_f32 v[164:165], v[164:165], v[174:175], v[172:173]
	v_pk_fma_f32 v[166:167], v[166:167], v[174:175], v[172:173]
	v_pk_fma_f32 v[168:169], v[168:169], v[174:175], v[172:173]
	v_pk_fma_f32 v[170:171], v[170:171], v[174:175], v[172:173]
	v_pk_mul_f32 v[144:145], v[144:145], v[194:195]
	v_pk_mul_f32 v[146:147], v[146:147], v[196:197]
	v_pk_mul_f32 v[148:149], v[148:149], v[198:199]
	v_pk_mul_f32 v[150:151], v[150:151], v[200:201]
	v_pk_mul_f32 v[164:165], v[164:165], v[202:203]
	v_pk_mul_f32 v[166:167], v[166:167], v[204:205]
	v_pk_mul_f32 v[168:169], v[168:169], v[206:207]
	v_pk_mul_f32 v[170:171], v[170:171], v[208:209]
	v_exp_f32_e32 v144, v144
	v_exp_f32_e32 v146, v146
	v_exp_f32_e32 v148, v148
	v_exp_f32_e32 v150, v150
	v_exp_f32_e32 v164, v164
	v_exp_f32_e32 v166, v166
	v_exp_f32_e32 v168, v168
	v_exp_f32_e32 v170, v170
	v_exp_f32_e32 v145, v145
	v_exp_f32_e32 v147, v147
	v_exp_f32_e32 v149, v149
	v_exp_f32_e32 v151, v151
	v_exp_f32_e32 v165, v165
	v_exp_f32_e32 v167, v167
	v_exp_f32_e32 v169, v169
	v_exp_f32_e32 v171, v171
	v_pk_add_f32 v[144:145], v[144:145], v[210:211]
	v_pk_add_f32 v[146:147], v[146:147], v[210:211]
	v_pk_add_f32 v[148:149], v[148:149], v[210:211]
	v_pk_add_f32 v[150:151], v[150:151], v[210:211]
	v_pk_add_f32 v[164:165], v[164:165], v[210:211]
	v_pk_add_f32 v[166:167], v[166:167], v[210:211]
	v_pk_add_f32 v[168:169], v[168:169], v[210:211]
	v_pk_add_f32 v[170:171], v[170:171], v[210:211]
	v_rcp_f32_e32 v144, v144
	v_rcp_f32_e32 v146, v146
	v_rcp_f32_e32 v148, v148
	v_rcp_f32_e32 v150, v150
	v_rcp_f32_e32 v164, v164
	v_rcp_f32_e32 v166, v166
	v_rcp_f32_e32 v168, v168
	v_rcp_f32_e32 v170, v170
	v_rcp_f32_e32 v145, v145
	v_rcp_f32_e32 v147, v147
	v_rcp_f32_e32 v149, v149
	v_rcp_f32_e32 v151, v151
	v_rcp_f32_e32 v165, v165
	v_rcp_f32_e32 v167, v167
	v_rcp_f32_e32 v169, v169
	v_rcp_f32_e32 v171, v171
	v_pk_mul_f32 v[52:53], v[194:195], v[44:45]
	v_pk_mul_f32 v[54:55], v[196:197], v[46:47]
	v_pk_mul_f32 v[36:37], v[198:199], v[28:29]
	v_pk_mul_f32 v[38:39], v[200:201], v[30:31]
	v_pk_mul_f32 v[32:33], v[202:203], v[24:25]
	v_pk_mul_f32 v[34:35], v[204:205], v[26:27]
	v_pk_mul_f32 v[48:49], v[206:207], v[4:5]
	v_pk_mul_f32 v[50:51], v[208:209], v[6:7]
	v_pk_mul_f32 v[52:53], v[52:53], v[144:145]
	v_pk_mul_f32 v[54:55], v[54:55], v[146:147]
	v_pk_mul_f32 v[36:37], v[36:37], v[148:149]
	v_pk_mul_f32 v[38:39], v[38:39], v[150:151]
	v_pk_mul_f32 v[32:33], v[32:33], v[164:165]
	v_pk_mul_f32 v[34:35], v[34:35], v[166:167]
	v_pk_mul_f32 v[48:49], v[48:49], v[168:169]
	v_pk_mul_f32 v[50:51], v[50:51], v[170:171]
	v_cvt_pk_bf16_f32 v60, v60, v61
	v_cvt_pk_bf16_f32 v61, v62, v63
	v_cvt_pk_bf16_f32 v62, v52, v53
	v_cvt_pk_bf16_f32 v63, v54, v55
	v_cvt_pk_bf16_f32 v20, v20, v21
	v_cvt_pk_bf16_f32 v21, v22, v23
	v_cvt_pk_bf16_f32 v22, v36, v37
	v_cvt_pk_bf16_f32 v23, v38, v39
	v_cvt_pk_bf16_f32 v16, v16, v17
	v_cvt_pk_bf16_f32 v17, v18, v19
	v_cvt_pk_bf16_f32 v18, v32, v33
	v_cvt_pk_bf16_f32 v19, v34, v35
	v_cvt_pk_bf16_f32 v56, v56, v57
	v_cvt_pk_bf16_f32 v57, v58, v59
	v_cvt_pk_bf16_f32 v58, v48, v49
	v_cvt_pk_bf16_f32 v59, v50, v51
	v_add_u32_e32 v235, 0x160000, v233
	s_mov_b64 exec, s[10:11]
	global_store_dwordx4 v235, v[60:63], s[18:19]
	s_mov_b64 exec, s[8:9]
	v_add_u32_e32 v235, 0x18c000, v233
	global_store_dwordx4 v235, v[20:23], s[18:19]
	v_add_u32_e32 v235, 0x1b8000, v233
	global_store_dwordx4 v235, v[16:19], s[18:19]
	v_add_u32_e32 v235, 0x1e4000, v233
	s_mov_b64 exec, s[62:63]
	global_store_dwordx4 v235, v[56:59], s[18:19]
	s_mov_b64 exec, s[8:9]
